# combo_placement_plus12B
# baseline (speedup 1.0000x reference)
.LBB0_466:
	s_nop 0
	s_nop 0
	s_nop 0
	s_add_i32 s57, s57, 1
	v_readlane_b32 s5, v253, 32
	v_readlane_b32 s10, v253, 0
	s_mul_i32 s5, s57, s5
	s_mul_hi_u32 s7, s57, s10
	s_add_i32 s7, s7, s5
	s_mul_i32 s5, s57, s10
	s_add_u32 s40, s5, s70
	v_readlane_b32 s5, v253, 33
	s_addc_u32 s41, s7, s5
	v_mov_b64_e32 v[2:3], s[78:79]
	v_readlane_b32 s11, v253, 1
	v_cmp_ge_i64_e32 vcc, s[40:41], v[2:3]
	v_cmp_lt_i64_e64 s[10:11], s[40:41], v[2:3]
	s_cbranch_vccnz .LBB0_468
	s_and_b32 s5, s40, 7
	s_ashr_i32 s7, s40, 3
	s_mul_i32 s5, s5, s58
	s_add_i32 s5, s5, s7
	s_abs_i32 s36, s5
	s_mul_hi_u32 s37, s36, s59
	s_mul_i32 s38, s37, s21
	s_sub_i32 s36, s36, s38
	s_ashr_i32 s33, s5, 31
	s_add_i32 s38, s37, 1
	s_sub_i32 s39, s36, s21
	s_cmp_ge_u32 s36, s21
	s_cselect_b32 s37, s38, s37
	s_cselect_b32 s36, s39, s36
	s_add_i32 s38, s37, 1
	s_cmp_ge_u32 s36, s21
	s_cselect_b32 s36, s38, s37
	s_xor_b32 s36, s36, s33
	s_sub_i32 s33, s36, s33
	s_mul_i32 s36, s33, s21
	s_sub_i32 s5, s5, s36
	s_lshl_b32 s33, s33, 3
	s_and_b32 s7, s7, 7
	s_or_b32 s36, s33, s7
	s_ashr_i32 s38, s5, 3
